# plus P7 hi/lo score MFMAs: K fragment ds_read_b128 pipelined 6 ahead through an 8-buffer ring (v136-v167)
# speedup vs baseline: 1.0087x; 1.0061x over previous
.LBB0_855:
	s_add_i32 s58, s58, s30
	s_cmpk_lt_i32 s58, 0x400
	s_cselect_b64 s[18:19], -1, 0
	s_cmpk_gt_i32 s58, 0x3ff
	s_cselect_b64 s[28:29], -1, 0
	s_and_b32 s22, s58, 63
	s_cmp_eq_u32 s22, 0
	s_cselect_b64 s[46:47], -1, 0
	s_and_b64 s[46:47], s[18:19], s[46:47]
	s_and_b64 vcc, exec, s[46:47]
	s_cbranch_vccnz .LBB0_855
	s_and_b32 s59, s50, 63
	v_cmp_gt_u32_e32 vcc, s59, v104
	s_waitcnt vmcnt(3)
	s_nop 0
	v_cndmask_b32_e32 v2, 0, v38, vcc
	v_bfe_u32 v3, v2, 16, 1
	v_add3_u32 v3, v2, v3, s55
	v_and_b32_e32 v4, 0xffff0000, v3
	v_sub_f32_e32 v6, v2, v4
	v_cndmask_b32_e32 v2, 0, v39, vcc
	v_bfe_u32 v4, v2, 16, 1
	v_add3_u32 v4, v2, v4, s55
	v_and_b32_e32 v4, 0xffff0000, v4
	v_sub_f32_e32 v7, v2, v4
	v_cndmask_b32_e32 v2, 0, v40, vcc
	v_bfe_u32 v5, v2, 16, 1
	v_add3_u32 v5, v2, v5, s55
	v_and_b32_e32 v8, 0xffff0000, v5
	v_sub_f32_e32 v8, v2, v8
	v_cndmask_b32_e32 v2, 0, v41, vcc
	v_bfe_u32 v9, v2, 16, 1
	v_add3_u32 v9, v2, v9, s55
	v_and_b32_e32 v9, 0xffff0000, v9
	v_sub_f32_e32 v10, v2, v9
	s_waitcnt vmcnt(2)
	v_cndmask_b32_e32 v2, 0, v58, vcc
	v_bfe_u32 v11, v2, 16, 1
	v_add3_u32 v11, v2, v11, s55
	v_and_b32_e32 v12, 0xffff0000, v11
	v_sub_f32_e32 v12, v2, v12
	v_cndmask_b32_e32 v2, 0, v59, vcc
	v_bfe_u32 v13, v2, 16, 1
	v_add3_u32 v13, v2, v13, s55
	v_and_b32_e32 v13, 0xffff0000, v13
	v_sub_f32_e32 v14, v2, v13
	v_cndmask_b32_e32 v2, 0, v60, vcc
	v_bfe_u32 v15, v2, 16, 1
	v_add3_u32 v15, v2, v15, s55
	v_and_b32_e32 v16, 0xffff0000, v15
	v_sub_f32_e32 v16, v2, v16
	v_cndmask_b32_e32 v2, 0, v61, vcc
	v_bfe_u32 v17, v2, 16, 1
	v_add3_u32 v17, v2, v17, s55
	v_and_b32_e32 v17, 0xffff0000, v17
	v_sub_f32_e32 v18, v2, v17
	v_or_b32_sdwa v2, v4, v3 dst_sel:DWORD dst_unused:UNUSED_PAD src0_sel:DWORD src1_sel:WORD_1
	v_or_b32_sdwa v3, v9, v5 dst_sel:DWORD dst_unused:UNUSED_PAD src0_sel:DWORD src1_sel:WORD_1
	v_or_b32_sdwa v4, v13, v11 dst_sel:DWORD dst_unused:UNUSED_PAD src0_sel:DWORD src1_sel:WORD_1
	v_or_b32_sdwa v5, v17, v15 dst_sel:DWORD dst_unused:UNUSED_PAD src0_sel:DWORD src1_sel:WORD_1
	v_cmp_gt_u32_e32 vcc, s59, v105
	v_cvt_pk_bf16_f32 v6, v6, v7
	v_cvt_pk_bf16_f32 v7, v8, v10
	v_cvt_pk_bf16_f32 v8, v12, v14
	v_cvt_pk_bf16_f32 v9, v16, v18
	ds_write_b128 v115, v[2:5]
	ds_write_b128 v115, v[6:9] offset:16384
	s_waitcnt vmcnt(1)
	v_cndmask_b32_e32 v2, 0, v74, vcc
	v_bfe_u32 v3, v2, 16, 1
	v_add3_u32 v3, v2, v3, s55
	v_and_b32_e32 v4, 0xffff0000, v3
	v_sub_f32_e32 v6, v2, v4
	v_cndmask_b32_e32 v2, 0, v75, vcc
	v_bfe_u32 v4, v2, 16, 1
	v_add3_u32 v4, v2, v4, s55
	v_and_b32_e32 v4, 0xffff0000, v4
	v_sub_f32_e32 v7, v2, v4
	v_cndmask_b32_e32 v2, 0, v76, vcc
	v_bfe_u32 v5, v2, 16, 1
	v_add3_u32 v5, v2, v5, s55
	v_and_b32_e32 v8, 0xffff0000, v5
	v_sub_f32_e32 v8, v2, v8
	v_cndmask_b32_e32 v2, 0, v77, vcc
	v_bfe_u32 v9, v2, 16, 1
	v_add3_u32 v9, v2, v9, s55
	v_and_b32_e32 v9, 0xffff0000, v9
	v_sub_f32_e32 v10, v2, v9
	s_waitcnt vmcnt(0)
	v_cndmask_b32_e32 v2, 0, v78, vcc
	v_bfe_u32 v11, v2, 16, 1
	v_add3_u32 v11, v2, v11, s55
	v_and_b32_e32 v12, 0xffff0000, v11
	v_sub_f32_e32 v12, v2, v12
	v_cndmask_b32_e32 v2, 0, v79, vcc
	v_bfe_u32 v13, v2, 16, 1
	v_add3_u32 v13, v2, v13, s55
	v_and_b32_e32 v13, 0xffff0000, v13
	v_sub_f32_e32 v14, v2, v13
	v_cndmask_b32_e32 v2, 0, v80, vcc
	v_bfe_u32 v15, v2, 16, 1
	v_add3_u32 v15, v2, v15, s55
	v_and_b32_e32 v16, 0xffff0000, v15
	v_sub_f32_e32 v16, v2, v16
	v_cndmask_b32_e32 v2, 0, v81, vcc
	v_bfe_u32 v17, v2, 16, 1
	v_add3_u32 v17, v2, v17, s55
	v_and_b32_e32 v17, 0xffff0000, v17
	v_sub_f32_e32 v18, v2, v17
	v_or_b32_sdwa v2, v4, v3 dst_sel:DWORD dst_unused:UNUSED_PAD src0_sel:DWORD src1_sel:WORD_1
	v_or_b32_sdwa v3, v9, v5 dst_sel:DWORD dst_unused:UNUSED_PAD src0_sel:DWORD src1_sel:WORD_1
	v_or_b32_sdwa v4, v13, v11 dst_sel:DWORD dst_unused:UNUSED_PAD src0_sel:DWORD src1_sel:WORD_1
	v_or_b32_sdwa v5, v17, v15 dst_sel:DWORD dst_unused:UNUSED_PAD src0_sel:DWORD src1_sel:WORD_1
	v_cvt_pk_bf16_f32 v6, v6, v7
	v_cvt_pk_bf16_f32 v7, v8, v10
	v_cvt_pk_bf16_f32 v8, v12, v14
	v_cvt_pk_bf16_f32 v9, v16, v18
	ds_write_b128 v116, v[2:5]
	ds_write_b128 v116, v[6:9] offset:16384
	s_and_saveexec_b64 s[46:47], s[16:17]
	ds_write_b32 v94, v87 offset:32768
	s_or_b64 exec, exec, s[46:47]
	s_waitcnt lgkmcnt(0)
	s_barrier
	ds_read_b128 v[136:139], v117
	ds_read_b128 v[140:143], v117 offset:8192
	ds_read_b128 v[144:147], v118
	ds_read_b128 v[148:151], v118 offset:8192
	ds_read_b128 v[152:155], v119
	ds_read_b128 v[156:159], v119 offset:8192
	ds_read_b128 v[160:163], v120
	ds_read_b128 v[164:167], v120 offset:8192
	s_waitcnt lgkmcnt(7)
	v_mfma_f32_32x32x16_bf16 v[18:33], v[136:139], v[34:37], 0
	s_andn2_b64 vcc, exec, s[18:19]
	s_waitcnt lgkmcnt(6)
	v_mfma_f32_32x32x16_bf16 v[2:17], v[140:143], v[34:37], 0
	ds_read_b128 v[136:139], v121
	s_waitcnt lgkmcnt(6)
	v_mfma_f32_32x32x16_bf16 v[18:33], v[144:147], v[42:45], v[18:33]
	ds_read_b128 v[140:143], v121 offset:8192
	s_waitcnt lgkmcnt(6)
	v_mfma_f32_32x32x16_bf16 v[2:17], v[148:151], v[42:45], v[2:17]
	ds_read_b128 v[144:147], v122
	s_waitcnt lgkmcnt(6)
	v_mfma_f32_32x32x16_bf16 v[18:33], v[152:155], v[46:49], v[18:33]
	ds_read_b128 v[148:151], v122 offset:8192
	s_waitcnt lgkmcnt(6)
	v_mfma_f32_32x32x16_bf16 v[2:17], v[156:159], v[46:49], v[2:17]
	ds_read_b128 v[152:155], v123
	s_waitcnt lgkmcnt(6)
	v_mfma_f32_32x32x16_bf16 v[18:33], v[160:163], v[50:53], v[18:33]
	ds_read_b128 v[156:159], v123 offset:8192
	s_waitcnt lgkmcnt(6)
	v_mfma_f32_32x32x16_bf16 v[2:17], v[164:167], v[50:53], v[2:17]
	ds_read_b128 v[160:163], v124
	s_waitcnt lgkmcnt(6)
	v_mfma_f32_32x32x16_bf16 v[18:33], v[136:139], v[54:57], v[18:33]
	ds_read_b128 v[164:167], v124 offset:8192
	s_waitcnt lgkmcnt(6)
	v_mfma_f32_32x32x16_bf16 v[2:17], v[140:143], v[54:57], v[2:17]
	ds_read_b128 v[136:139], v117 offset:16384
	s_waitcnt lgkmcnt(6)
	v_mfma_f32_32x32x16_bf16 v[18:33], v[144:147], v[62:65], v[18:33]
	ds_read_b128 v[140:143], v117 offset:24576
	s_waitcnt lgkmcnt(6)
	v_mfma_f32_32x32x16_bf16 v[2:17], v[148:151], v[62:65], v[2:17]
	ds_read_b128 v[144:147], v118 offset:16384
	s_waitcnt lgkmcnt(6)
	v_mfma_f32_32x32x16_bf16 v[18:33], v[152:155], v[66:69], v[18:33]
	ds_read_b128 v[148:151], v118 offset:24576
	s_waitcnt lgkmcnt(6)
	v_mfma_f32_32x32x16_bf16 v[2:17], v[156:159], v[66:69], v[2:17]
	ds_read_b128 v[152:155], v119 offset:16384
	s_waitcnt lgkmcnt(6)
	v_mfma_f32_32x32x16_bf16 v[18:33], v[160:163], v[70:73], v[18:33]
	ds_read_b128 v[156:159], v119 offset:24576
	s_waitcnt lgkmcnt(6)
	v_mfma_f32_32x32x16_bf16 v[2:17], v[164:167], v[70:73], v[2:17]
	ds_read_b128 v[160:163], v120 offset:16384
	s_waitcnt lgkmcnt(6)
	v_mfma_f32_32x32x16_bf16 v[18:33], v[136:139], v[34:37], v[18:33]
	ds_read_b128 v[164:167], v120 offset:24576
	s_waitcnt lgkmcnt(6)
	v_mfma_f32_32x32x16_bf16 v[2:17], v[140:143], v[34:37], v[2:17]
	ds_read_b128 v[136:139], v121 offset:16384
	s_waitcnt lgkmcnt(6)
	v_mfma_f32_32x32x16_bf16 v[18:33], v[144:147], v[42:45], v[18:33]
	ds_read_b128 v[140:143], v121 offset:24576
	s_waitcnt lgkmcnt(6)
	v_mfma_f32_32x32x16_bf16 v[2:17], v[148:151], v[42:45], v[2:17]
	ds_read_b128 v[144:147], v122 offset:16384
	s_waitcnt lgkmcnt(6)
	v_mfma_f32_32x32x16_bf16 v[18:33], v[152:155], v[46:49], v[18:33]
	ds_read_b128 v[148:151], v122 offset:24576
	s_waitcnt lgkmcnt(6)
	v_mfma_f32_32x32x16_bf16 v[2:17], v[156:159], v[46:49], v[2:17]
	ds_read_b128 v[152:155], v123 offset:16384
	s_waitcnt lgkmcnt(6)
	v_mfma_f32_32x32x16_bf16 v[18:33], v[160:163], v[50:53], v[18:33]
	ds_read_b128 v[156:159], v123 offset:24576
	s_waitcnt lgkmcnt(6)
	v_mfma_f32_32x32x16_bf16 v[2:17], v[164:167], v[50:53], v[2:17]
	ds_read_b128 v[160:163], v124 offset:16384
	s_waitcnt lgkmcnt(6)
	v_mfma_f32_32x32x16_bf16 v[18:33], v[136:139], v[54:57], v[18:33]
	ds_read_b128 v[164:167], v124 offset:24576
	s_waitcnt lgkmcnt(6)
	v_mfma_f32_32x32x16_bf16 v[2:17], v[140:143], v[54:57], v[2:17]
	s_waitcnt lgkmcnt(5)
	v_mfma_f32_32x32x16_bf16 v[18:33], v[144:147], v[62:65], v[18:33]
	s_waitcnt lgkmcnt(4)
	v_mfma_f32_32x32x16_bf16 v[2:17], v[148:151], v[62:65], v[2:17]
	s_waitcnt lgkmcnt(3)
	v_mfma_f32_32x32x16_bf16 v[18:33], v[152:155], v[66:69], v[18:33]
	s_waitcnt lgkmcnt(2)
	v_mfma_f32_32x32x16_bf16 v[2:17], v[156:159], v[66:69], v[2:17]
	s_waitcnt lgkmcnt(1)
	v_mfma_f32_32x32x16_bf16 v[18:33], v[160:163], v[70:73], v[18:33]
	s_waitcnt lgkmcnt(0)
	v_mfma_f32_32x32x16_bf16 v[2:17], v[164:167], v[70:73], v[2:17]
	s_cbranch_vccnz .LBB0_860
	s_ashr_i32 s18, s58, 9
	s_bfe_u32 s60, s58, 0x30006
	s_lshl_b32 s19, s18, 3
	s_or_b32 s46, s19, s60
	s_ashr_i32 s47, s46, 31
	s_ashr_i32 s19, s18, 31
	s_lshl_b64 s[46:47], s[46:47], 15
	s_lshl_b64 s[18:19], s[18:19], 25
	v_lshl_add_u32 v86, s22, 8, v1
	s_add_u32 s18, s48, s18
	v_lshlrev_b64 v[34:35], 11, v[86:87]
	s_addc_u32 s19, s49, s19
	v_lshl_add_u64 v[34:35], s[18:19], 0, v[34:35]
	s_lshl_b32 s22, s60, 8
	v_lshl_add_u64 v[34:35], v[34:35], 0, s[22:23]
	v_mov_b32_e32 v83, v87
	v_lshl_add_u64 v[38:39], v[34:35], 0, v[82:83]
	global_load_dwordx4 v[34:37], v[38:39], off
	global_load_dwordx4 v[42:45], v[38:39], off offset:32
	global_load_dwordx4 v[46:49], v[38:39], off offset:64
	global_load_dwordx4 v[50:53], v[38:39], off offset:96
	global_load_dwordx4 v[54:57], v[38:39], off offset:128
	global_load_dwordx4 v[62:65], v[38:39], off offset:160
	global_load_dwordx4 v[66:69], v[38:39], off offset:192
	global_load_dwordx4 v[70:73], v[38:39], off offset:224
	v_lshl_add_u64 v[38:39], v[90:91], 0, s[46:47]
	v_mov_b32_e32 v85, v87
	v_lshl_add_u64 v[74:75], v[38:39], 0, v[84:85]
	global_load_dwordx4 v[38:41], v[74:75], off
	global_load_dwordx4 v[58:61], v[74:75], off offset:16
	v_lshl_add_u64 v[78:79], v[74:75], 0, s[26:27]
	v_add_co_u32_e32 v74, vcc, s56, v74
	s_nop 1
	v_addc_co_u32_e32 v75, vcc, 0, v75, vcc
	global_load_dwordx4 v[74:77], v[74:75], off
	s_nop 0
	global_load_dwordx4 v[78:81], v[78:79], off offset:16
